# attention: batch GB epilogue loads, batch QK/PV ds_reads ahead of MFMAs
# speedup vs baseline: 1.0150x; 1.0150x over previous
; __device__ __forceinline__ float sigm(float x) { return __builtin_amdgcn_rcpf(1.f + __builtin_amdgcn_exp2f(-1.4426950408889634f * x)); }
; __device__ __forceinline__ u32x4 pack8(const f32x4 a, const f32x4 b) { u32x4 w; w.x = cvt_pk_bf16(a[0], a[1]); w.y = cvt_pk_bf16(a[2], a[3]); w.z = cvt_pk_bf16(b[0], b[1]); w.w = cvt_pk_bf16(b[2], b[3]); return w; }
; #define LAS __attribute__((address_space(3)))
;     ...
;     LAS float* stg = (LAS float*)(lds + AT_STG + wid * AT_STG_W);
; #pragma unroll
;     for (int g4 = 0; g4 < 4; ++g4) {
;         *(LAS f32x4*)(stg + r32 * 68 + 8 * g4 + 4 * hi) = (f32x4){o0[4 * g4], o0[4 * g4 + 1], o0[4 * g4 + 2], o0[4 * g4 + 3]};
;         *(LAS f32x4*)(stg + r32 * 68 + 32 + 8 * g4 + 4 * hi) = (f32x4){o1[4 * g4], o1[4 * g4 + 1], o1[4 * g4 + 2], o1[4 * g4 + 3]};
;     }
;     asm volatile("s_waitcnt lgkmcnt(0)" ::: "memory");
; #pragma unroll
;     for (int i = 0; i < 4; ++i) {
;         const int row = i * 8 + (lane >> 3), ch = lane & 7;
;         f32x4 a0 = *(const LAS f32x4*)(stg + row * 68 + ch * 8), a1 = *(const LAS f32x4*)(stg + row * 68 + ch * 8 + 4);
;         const size_t tok = rowbase + qw + row;
;         const u32x4 gw_ = *(const u32x4*)(GBb + tok * 1024 + h * HD + ch * 8);
;         f32x4 g0, g1; pg8::unpack8(gw_, g0, g1);
; #pragma unroll
;         for (int e = 0; e < 4; ++e) { a0[e] *= g0[e] * pg8::sigm(g0[e]); a1[e] *= g1[e] * pg8::sigm(g1[e]); }
;         if (!dry) *(u32x4*)(UGQ + tok * 2048 + 1024 + h * HD + ch * 8) = pg8::pack8(a0, a1);
;     }
.LBB0_456:
	s_mulk_i32 s33, 0x1e00
	s_add_i32 s20, s20, s33
	v_mul_u32_u24_e32 v32, 0x110, v106
	v_add3_u32 v32, s20, v32, v64
	ds_write_b128 v32, v[16:19] offset:34816
	ds_write_b128 v32, v[0:3] offset:34944
	ds_write_b128 v32, v[20:23] offset:34848
	ds_write_b128 v32, v[4:7] offset:34976
	ds_write_b128 v32, v[24:27] offset:34880
	ds_write_b128 v32, v[8:11] offset:35008
	ds_write_b128 v32, v[28:31] offset:34912
	ds_write_b128 v32, v[12:15] offset:35040
	v_lshlrev_b32_e32 v0, 3, v104
	v_lshrrev_b32_e32 v8, 3, v105
	v_and_b32_e32 v0, 56, v0
	v_lshlrev_b32_e32 v1, 2, v0
	v_lshlrev_b32_e32 v64, 1, v0
	v_mul_u32_u24_e32 v0, 0x110, v8
	v_or_b32_e32 v8, s10, v8
	v_mov_b32_e32 v9, s11
	v_lshl_add_u64 v[10:11], s[14:15], 0, v[64:65]
	v_lshlrev_b64 v[12:13], 11, v[8:9]
	s_waitcnt lgkmcnt(0)
	v_add3_u32 v14, s20, v1, v0
	v_lshl_add_u64 v[12:13], v[10:11], 0, v[12:13]
	ds_read_b128 v[0:3], v14 offset:34816
	ds_read_b128 v[4:7], v14 offset:34832
	global_load_dwordx4 v[16:19], v[12:13], off
	v_add_co_u32_e32 v154, vcc, 0x4000, v12
	s_nop 1
	v_addc_co_u32_e32 v155, vcc, 0, v13, vcc
	global_load_dwordx4 v[142:145], v[154:155], off
	v_add_co_u32_e32 v154, vcc, 0x8000, v12
	s_nop 1
	v_addc_co_u32_e32 v155, vcc, 0, v13, vcc
	global_load_dwordx4 v[146:149], v[154:155], off
	v_add_co_u32_e32 v154, vcc, 0xc000, v12
	s_nop 1
	v_addc_co_u32_e32 v155, vcc, 0, v13, vcc
	global_load_dwordx4 v[150:153], v[154:155], off
	s_mov_b64 s[4:5], 0
	s_and_b64 vcc, exec, s[28:29]
	s_waitcnt vmcnt(3)
	v_lshlrev_b32_e32 v12, 16, v16
	v_mul_f32_e32 v15, 0xbfb8aa3b, v12
	v_exp_f32_e32 v15, v15
	v_and_b32_e32 v13, 0xffff0000, v16
	v_add_f32_e32 v15, 1.0, v15
	v_rcp_f32_e32 v20, v15
	v_mul_f32_e32 v15, 0xbfb8aa3b, v13
	v_exp_f32_e32 v15, v15
	s_nop 0
	v_add_f32_e32 v15, 1.0, v15
	v_rcp_f32_e32 v21, v15
	s_nop 0
	v_pk_mul_f32 v[12:13], v[20:21], v[12:13]
	s_waitcnt lgkmcnt(1)
	v_pk_mul_f32 v[0:1], v[0:1], v[12:13]
	v_lshlrev_b32_e32 v12, 16, v18
	v_mul_f32_e32 v15, 0xbfb8aa3b, v12
	v_exp_f32_e32 v15, v15
	v_and_b32_e32 v13, 0xffff0000, v18
	v_cvt_pk_bf16_f32 v0, v0, v1
	v_add_f32_e32 v15, 1.0, v15
	v_rcp_f32_e32 v20, v15
	v_mul_f32_e32 v15, 0xbfb8aa3b, v13
	v_exp_f32_e32 v15, v15
	s_nop 0
	v_add_f32_e32 v15, 1.0, v15
	v_rcp_f32_e32 v21, v15
	s_nop 0
	v_pk_mul_f32 v[12:13], v[20:21], v[12:13]
	s_waitcnt lgkmcnt(0)
	v_pk_mul_f32 v[4:5], v[4:5], v[12:13]
	v_lshlrev_b32_e32 v12, 16, v17
	v_mul_f32_e32 v15, 0xbfb8aa3b, v12
	v_exp_f32_e32 v15, v15
	v_and_b32_e32 v13, 0xffff0000, v17
	v_add_f32_e32 v15, 1.0, v15
	v_rcp_f32_e32 v16, v15
	v_mul_f32_e32 v15, 0xbfb8aa3b, v13
	v_exp_f32_e32 v15, v15
	s_nop 0
	v_add_f32_e32 v15, 1.0, v15
	v_rcp_f32_e32 v17, v15
	s_nop 0
	v_pk_mul_f32 v[12:13], v[16:17], v[12:13]
	s_nop 0
	v_pk_mul_f32 v[2:3], v[2:3], v[12:13]
	v_lshlrev_b32_e32 v12, 16, v19
	v_mul_f32_e32 v15, 0xbfb8aa3b, v12
	v_exp_f32_e32 v15, v15
	v_and_b32_e32 v13, 0xffff0000, v19
	v_cvt_pk_bf16_f32 v1, v2, v3
	v_cvt_pk_bf16_f32 v2, v4, v5
	v_add_f32_e32 v15, 1.0, v15
	v_rcp_f32_e32 v16, v15
	v_mul_f32_e32 v15, 0xbfb8aa3b, v13
	v_exp_f32_e32 v15, v15
	v_lshlrev_b64 v[4:5], 12, v[8:9]
	v_lshl_add_u64 v[4:5], s[30:31], 0, v[4:5]
	v_lshl_add_u64 v[4:5], v[4:5], 0, v[64:65]
	v_add_f32_e32 v15, 1.0, v15
	v_rcp_f32_e32 v17, v15
	s_nop 0
	v_pk_mul_f32 v[12:13], v[16:17], v[12:13]
	s_nop 0
	v_pk_mul_f32 v[6:7], v[6:7], v[12:13]
	v_or_b32_e32 v12, 8, v8
	v_mov_b32_e32 v13, s11
	v_cvt_pk_bf16_f32 v3, v6, v7
	v_lshlrev_b64 v[16:17], 11, v[12:13]
	global_store_dwordx4 v[4:5], v[0:3], off offset:2048
	v_lshl_add_u64 v[16:17], v[10:11], 0, v[16:17]
	ds_read_b128 v[4:7], v14 offset:36992
	ds_read_b128 v[0:3], v14 offset:37008
	s_waitcnt vmcnt(3)
	v_mov_b32_e32 v16, v142
	v_mov_b32_e32 v17, v143
	v_mov_b32_e32 v18, v144
	v_mov_b32_e32 v19, v145
	v_lshlrev_b32_e32 v20, 16, v16
	v_mul_f32_e32 v15, 0xbfb8aa3b, v20
	v_exp_f32_e32 v15, v15
	v_and_b32_e32 v21, 0xffff0000, v16
	v_add_f32_e32 v15, 1.0, v15
	v_rcp_f32_e32 v22, v15
	v_mul_f32_e32 v15, 0xbfb8aa3b, v21
	v_exp_f32_e32 v15, v15
	s_nop 0
	v_add_f32_e32 v15, 1.0, v15
	v_rcp_f32_e32 v23, v15
	s_nop 0
	v_pk_mul_f32 v[20:21], v[22:23], v[20:21]
	s_waitcnt lgkmcnt(1)
	v_pk_mul_f32 v[4:5], v[4:5], v[20:21]
	v_lshlrev_b32_e32 v20, 16, v18
	v_mul_f32_e32 v15, 0xbfb8aa3b, v20
	v_exp_f32_e32 v15, v15
	v_and_b32_e32 v21, 0xffff0000, v18
	v_add_f32_e32 v15, 1.0, v15
	v_rcp_f32_e32 v22, v15
	v_mul_f32_e32 v15, 0xbfb8aa3b, v21
	v_exp_f32_e32 v15, v15
	s_nop 0
	v_add_f32_e32 v15, 1.0, v15
	v_rcp_f32_e32 v23, v15
	s_nop 0
	v_pk_mul_f32 v[20:21], v[22:23], v[20:21]
	s_waitcnt lgkmcnt(0)
; __device__ __forceinline__ float sigm(float x) { return __builtin_amdgcn_rcpf(1.f + __builtin_amdgcn_exp2f(-1.4426950408889634f * x)); }
; __device__ __forceinline__ u32x4 pack8(const f32x4 a, const f32x4 b) { u32x4 w; w.x = cvt_pk_bf16(a[0], a[1]); w.y = cvt_pk_bf16(a[2], a[3]); w.z = cvt_pk_bf16(b[0], b[1]); w.w = cvt_pk_bf16(b[2], b[3]); return w; }
; #define LAS __attribute__((address_space(3)))
;     ...
;     for (int i = 0; i < 4; ++i) {
;         const int row = i * 8 + (lane >> 3), ch = lane & 7;
;         f32x4 a0 = *(const LAS f32x4*)(stg + row * 68 + ch * 8), a1 = *(const LAS f32x4*)(stg + row * 68 + ch * 8 + 4);
;         const size_t tok = rowbase + qw + row;
;         const u32x4 gw_ = *(const u32x4*)(GBb + tok * 1024 + h * HD + ch * 8);
;         f32x4 g0, g1; pg8::unpack8(gw_, g0, g1);
; #pragma unroll
;         for (int e = 0; e < 4; ++e) { a0[e] *= g0[e] * pg8::sigm(g0[e]); a1[e] *= g1[e] * pg8::sigm(g1[e]); }
;         if (!dry) *(u32x4*)(UGQ + tok * 2048 + 1024 + h * HD + ch * 8) = pg8::pack8(a0, a1);
;     }
	v_pk_mul_f32 v[20:21], v[0:1], v[20:21]
	v_lshlrev_b32_e32 v0, 16, v17
	v_mul_f32_e32 v15, 0xbfb8aa3b, v0
	v_exp_f32_e32 v15, v15
	v_and_b32_e32 v1, 0xffff0000, v17
	v_add_f32_e32 v15, 1.0, v15
	v_rcp_f32_e32 v16, v15
	v_mul_f32_e32 v15, 0xbfb8aa3b, v1
	v_exp_f32_e32 v15, v15
	s_nop 0
	v_add_f32_e32 v15, 1.0, v15
	v_rcp_f32_e32 v17, v15
	s_nop 0
	v_pk_mul_f32 v[0:1], v[16:17], v[0:1]
	s_nop 0
	v_pk_mul_f32 v[6:7], v[6:7], v[0:1]
	v_lshlrev_b32_e32 v0, 16, v19
	v_mul_f32_e32 v15, 0xbfb8aa3b, v0
	v_exp_f32_e32 v15, v15
	v_and_b32_e32 v1, 0xffff0000, v19
	v_add_f32_e32 v15, 1.0, v15
	v_rcp_f32_e32 v16, v15
	v_mul_f32_e32 v15, 0xbfb8aa3b, v1
	v_exp_f32_e32 v15, v15
	s_nop 0
	v_add_f32_e32 v15, 1.0, v15
	v_rcp_f32_e32 v17, v15
	s_nop 0
	v_pk_mul_f32 v[0:1], v[16:17], v[0:1]
	s_nop 0
	v_pk_mul_f32 v[16:17], v[2:3], v[0:1]
	v_cvt_pk_bf16_f32 v0, v4, v5
	v_lshlrev_b64 v[4:5], 12, v[12:13]
	v_lshl_add_u64 v[4:5], s[30:31], 0, v[4:5]
	v_or_b32_e32 v12, 16, v8
	v_cvt_pk_bf16_f32 v1, v6, v7
	v_cvt_pk_bf16_f32 v2, v20, v21
	v_cvt_pk_bf16_f32 v3, v16, v17
	v_lshl_add_u64 v[4:5], v[4:5], 0, v[64:65]
	v_lshlrev_b64 v[16:17], 11, v[12:13]
	global_store_dwordx4 v[4:5], v[0:3], off offset:2048
	v_lshl_add_u64 v[16:17], v[10:11], 0, v[16:17]
	ds_read_b128 v[4:7], v14 offset:39168
	ds_read_b128 v[0:3], v14 offset:39184
	v_or_b32_e32 v8, 24, v8
	s_waitcnt vmcnt(3)
	v_mov_b32_e32 v16, v146
	v_mov_b32_e32 v17, v147
	v_mov_b32_e32 v18, v148
	v_mov_b32_e32 v19, v149
	v_lshlrev_b32_e32 v20, 16, v16
	v_mul_f32_e32 v15, 0xbfb8aa3b, v20
	v_exp_f32_e32 v15, v15
	v_and_b32_e32 v21, 0xffff0000, v16
	v_add_f32_e32 v15, 1.0, v15
	v_rcp_f32_e32 v22, v15
	v_mul_f32_e32 v15, 0xbfb8aa3b, v21
	v_exp_f32_e32 v15, v15
	s_nop 0
	v_add_f32_e32 v15, 1.0, v15
	v_rcp_f32_e32 v23, v15
	s_nop 0
	v_pk_mul_f32 v[20:21], v[22:23], v[20:21]
	s_waitcnt lgkmcnt(1)
	v_pk_mul_f32 v[4:5], v[4:5], v[20:21]
	v_lshlrev_b32_e32 v20, 16, v18
	v_mul_f32_e32 v15, 0xbfb8aa3b, v20
	v_exp_f32_e32 v15, v15
	v_and_b32_e32 v21, 0xffff0000, v18
	v_add_f32_e32 v15, 1.0, v15
	v_rcp_f32_e32 v22, v15
	v_mul_f32_e32 v15, 0xbfb8aa3b, v21
	v_exp_f32_e32 v15, v15
	s_nop 0
	v_add_f32_e32 v15, 1.0, v15
	v_rcp_f32_e32 v23, v15
	s_nop 0
	v_pk_mul_f32 v[20:21], v[22:23], v[20:21]
	s_waitcnt lgkmcnt(0)
	v_pk_mul_f32 v[20:21], v[0:1], v[20:21]
	v_lshlrev_b32_e32 v0, 16, v17
	v_mul_f32_e32 v15, 0xbfb8aa3b, v0
	v_exp_f32_e32 v15, v15
	v_and_b32_e32 v1, 0xffff0000, v17
	v_add_f32_e32 v15, 1.0, v15
	v_rcp_f32_e32 v16, v15
	v_mul_f32_e32 v15, 0xbfb8aa3b, v1
	v_exp_f32_e32 v15, v15
	s_nop 0
	v_add_f32_e32 v15, 1.0, v15
	v_rcp_f32_e32 v17, v15
	s_nop 0
	v_pk_mul_f32 v[0:1], v[16:17], v[0:1]
	s_nop 0
	v_pk_mul_f32 v[6:7], v[6:7], v[0:1]
	v_lshlrev_b32_e32 v0, 16, v19
	v_mul_f32_e32 v15, 0xbfb8aa3b, v0
	v_exp_f32_e32 v15, v15
	v_and_b32_e32 v1, 0xffff0000, v19
	v_add_f32_e32 v15, 1.0, v15
	v_rcp_f32_e32 v16, v15
	v_mul_f32_e32 v15, 0xbfb8aa3b, v1
	v_exp_f32_e32 v15, v15
	s_nop 0
	v_add_f32_e32 v15, 1.0, v15
	v_rcp_f32_e32 v17, v15
	s_nop 0
	v_pk_mul_f32 v[0:1], v[16:17], v[0:1]
	s_nop 0
	v_pk_mul_f32 v[16:17], v[2:3], v[0:1]
	v_cvt_pk_bf16_f32 v0, v4, v5
	v_lshlrev_b64 v[4:5], 12, v[12:13]
	v_lshl_add_u64 v[4:5], s[30:31], 0, v[4:5]
	v_cvt_pk_bf16_f32 v1, v6, v7
	v_cvt_pk_bf16_f32 v2, v20, v21
	v_cvt_pk_bf16_f32 v3, v16, v17
	v_lshl_add_u64 v[4:5], v[4:5], 0, v[64:65]
	v_lshlrev_b64 v[12:13], 11, v[8:9]
	global_store_dwordx4 v[4:5], v[0:3], off offset:2048
	v_lshl_add_u64 v[10:11], v[10:11], 0, v[12:13]
	ds_read_b128 v[4:7], v14 offset:41344
	ds_read_b128 v[0:3], v14 offset:41360
	s_waitcnt vmcnt(3)
	v_mov_b32_e32 v10, v150
	v_mov_b32_e32 v11, v151
	v_mov_b32_e32 v12, v152
	v_mov_b32_e32 v13, v153
	v_lshlrev_b32_e32 v14, 16, v10
	v_and_b32_e32 v15, 0xffff0000, v10
	v_mul_f32_e32 v10, 0xbfb8aa3b, v14
	v_exp_f32_e32 v10, v10
	s_nop 0
	v_add_f32_e32 v10, 1.0, v10
	v_rcp_f32_e32 v16, v10
	v_mul_f32_e32 v10, 0xbfb8aa3b, v15
	v_exp_f32_e32 v10, v10
	s_nop 0
	v_add_f32_e32 v10, 1.0, v10
	v_rcp_f32_e32 v17, v10
	s_nop 0
	v_pk_mul_f32 v[14:15], v[16:17], v[14:15]
	s_waitcnt lgkmcnt(1)
	v_pk_mul_f32 v[4:5], v[4:5], v[14:15]
	v_lshlrev_b32_e32 v14, 16, v12
	v_mul_f32_e32 v10, 0xbfb8aa3b, v14
	v_exp_f32_e32 v10, v10
	v_and_b32_e32 v15, 0xffff0000, v12
	v_add_f32_e32 v10, 1.0, v10
	v_rcp_f32_e32 v16, v10
	v_mul_f32_e32 v10, 0xbfb8aa3b, v15
	v_exp_f32_e32 v10, v10
	s_nop 0
	v_add_f32_e32 v10, 1.0, v10
	v_rcp_f32_e32 v17, v10
	s_nop 0
	v_pk_mul_f32 v[14:15], v[16:17], v[14:15]
	s_waitcnt lgkmcnt(0)
	v_pk_mul_f32 v[14:15], v[0:1], v[14:15]
	v_lshlrev_b32_e32 v0, 16, v11
	v_and_b32_e32 v1, 0xffff0000, v11
	v_mul_f32_e32 v10, 0xbfb8aa3b, v0
	v_mul_f32_e32 v11, 0xbfb8aa3b, v1
	v_exp_f32_e32 v10, v10
	v_exp_f32_e32 v11, v11
	v_add_f32_e32 v10, 1.0, v10
	v_add_f32_e32 v11, 1.0, v11
	v_rcp_f32_e32 v10, v10
	v_rcp_f32_e32 v11, v11
	s_nop 0
	v_pk_mul_f32 v[0:1], v[10:11], v[0:1]
	s_nop 0
	v_pk_mul_f32 v[6:7], v[6:7], v[0:1]
	v_lshlrev_b32_e32 v0, 16, v13
	v_and_b32_e32 v1, 0xffff0000, v13
	v_mul_f32_e32 v10, 0xbfb8aa3b, v0
	v_mul_f32_e32 v11, 0xbfb8aa3b, v1
	v_exp_f32_e32 v10, v10
	v_exp_f32_e32 v11, v11
	v_add_f32_e32 v10, 1.0, v10
	v_add_f32_e32 v11, 1.0, v11
	v_rcp_f32_e32 v10, v10
	v_rcp_f32_e32 v11, v11
	s_nop 0
	v_pk_mul_f32 v[0:1], v[10:11], v[0:1]
	s_nop 0
	v_pk_mul_f32 v[10:11], v[2:3], v[0:1]
	v_cvt_pk_bf16_f32 v0, v4, v5
	v_lshlrev_b64 v[4:5], 12, v[8:9]
	v_lshl_add_u64 v[4:5], s[30:31], 0, v[4:5]
	v_cvt_pk_bf16_f32 v1, v6, v7
	v_cvt_pk_bf16_f32 v2, v14, v15
	v_cvt_pk_bf16_f32 v3, v10, v11
	v_lshl_add_u64 v[4:5], v[4:5], 0, v[64:65]
	global_store_dwordx4 v[4:5], v[0:3], off offset:2048
	s_waitcnt lgkmcnt(0)
	s_cbranch_vccnz .LBB0_454

; #define LAS __attribute__((address_space(3)))
;     ...
;         if (k0 < qw + 32 && alive) {
;             const LAS unsigned char* kb = lds + AT_K + cur * 8192 + hi * 1024 + r32 * 16;
;             f32x16 p0, p1;
; #pragma unroll
;             for (int r = 0; r < 16; ++r) { p0[r] = 0.f; p1[r] = 0.f; }
; #pragma unroll
;             for (int d0 = 0; d0 < 4; ++d0) {
;                 const bf16x8 a0 = *(const LAS bf16x8*)(kb + d0 * 2048), a1 = *(const LAS bf16x8*)(kb + d0 * 2048 + 512);
;                 p0 = __builtin_amdgcn_mfma_f32_32x32x16_bf16(a0, qr[d0], p0, 0, 0, 0);
;                 p1 = __builtin_amdgcn_mfma_f32_32x32x16_bf16(a1, qr[d0], p1, 0, 0, 0);
;             }
; #pragma unroll
;             for (int r = 0; r < 16; ++r) { p0[r] = __builtin_amdgcn_rcpf(1.f + __builtin_amdgcn_exp2f(p0[r])); p1[r] = __builtin_amdgcn_rcpf(1.f + __builtin_amdgcn_exp2f(p1[r])); }
.LBB0_461:
	s_and_b32 s1, s6, 1
	s_cmp_le_i32 s27, s24
	s_cselect_b64 s[4:5], -1, 0
	v_cmp_ne_u32_e32 vcc, 0, v32
	s_and_b64 s[4:5], s[4:5], vcc
	s_andn2_b64 vcc, exec, s[4:5]
	s_cbranch_vccnz .LBB0_471
	v_lshl_add_u32 v94, s1, 13, v111
	s_mul_i32 s98, s1, 0x2400
	ds_read_b128 v[156:159], v94
	ds_read_b128 v[160:163], v94 offset:2048
	ds_read_b128 v[168:171], v94 offset:4096
	ds_read_b128 v[172:175], v94 offset:6144
	ds_read_b128 v[176:179], v94 offset:512
	ds_read_b128 v[180:183], v94 offset:2560
	ds_read_b128 v[184:187], v94 offset:4608
	ds_read_b128 v[188:191], v94 offset:6656
	v_add_u32_e32 v126, s98, v112
	s_add_i32 s4, s27, 63
	s_cmp_lt_i32 s4, s24
	s_waitcnt lgkmcnt(7)
	v_mfma_f32_32x32x16_bf16 v[32:47], v[156:159], v[66:69], 0
	ds_read_b128 v[206:209], v126 offset:16384
	s_waitcnt lgkmcnt(7)
	v_mfma_f32_32x32x16_bf16 v[32:47], v[160:163], v[70:73], v[32:47]
	ds_read_b128 v[210:213], v126 offset:20992
	s_waitcnt lgkmcnt(7)
	v_mfma_f32_32x32x16_bf16 v[32:47], v[168:171], v[74:77], v[32:47]
	ds_read_b128 v[214:217], v126 offset:16400
	s_waitcnt lgkmcnt(7)
	v_mfma_f32_32x32x16_bf16 v[32:47], v[172:175], v[78:81], v[32:47]
	ds_read_b128 v[218:221], v126 offset:21008
	s_waitcnt lgkmcnt(7)
	v_mfma_f32_32x32x16_bf16 v[48:63], v[176:179], v[66:69], 0
	ds_read_b128 v[222:225], v126 offset:16448
	s_waitcnt lgkmcnt(7)
	v_mfma_f32_32x32x16_bf16 v[48:63], v[180:183], v[70:73], v[48:63]
	ds_read_b128 v[226:229], v126 offset:21056
	s_waitcnt lgkmcnt(7)
	v_mfma_f32_32x32x16_bf16 v[48:63], v[184:187], v[74:77], v[48:63]
	ds_read_b128 v[118:121], v126 offset:16464
	s_waitcnt lgkmcnt(7)
	v_mfma_f32_32x32x16_bf16 v[48:63], v[188:191], v[78:81], v[48:63]
	ds_read_b128 v[122:125], v126 offset:21072
	s_nop 8
	v_exp_f32_e32 v34, v34
	v_exp_f32_e32 v32, v32
	v_exp_f32_e32 v33, v33
	v_add_f32_e32 v34, 1.0, v34
	v_add_f32_e32 v32, 1.0, v32
	v_add_f32_e32 v33, 1.0, v33
	v_exp_f32_e32 v48, v48
	v_rcp_f32_e32 v32, v32
	v_rcp_f32_e32 v33, v33
	v_add_f32_e32 v48, 1.0, v48
	v_rcp_f32_e32 v96, v48
	v_exp_f32_e32 v48, v49
	v_exp_f32_e32 v49, v50
	v_add_f32_e32 v48, 1.0, v48
	v_rcp_f32_e32 v97, v48
	v_rcp_f32_e32 v48, v34
	v_exp_f32_e32 v34, v35
	v_add_f32_e32 v35, 1.0, v49
	v_rcp_f32_e32 v98, v35
	v_exp_f32_e32 v35, v51
	v_add_f32_e32 v34, 1.0, v34
	v_rcp_f32_e32 v49, v34
	v_exp_f32_e32 v34, v36
	v_add_f32_e32 v35, 1.0, v35
	v_rcp_f32_e32 v99, v35
	v_exp_f32_e32 v35, v52
	v_add_f32_e32 v34, 1.0, v34
	v_rcp_f32_e32 v50, v34
	v_exp_f32_e32 v34, v37
	v_add_f32_e32 v35, 1.0, v35
	v_rcp_f32_e32 v52, v35
	v_exp_f32_e32 v35, v53
	v_add_f32_e32 v34, 1.0, v34
	v_rcp_f32_e32 v51, v34
	v_exp_f32_e32 v34, v38
	v_add_f32_e32 v35, 1.0, v35
	v_rcp_f32_e32 v53, v35
	v_exp_f32_e32 v35, v54
	v_add_f32_e32 v34, 1.0, v34
	v_rcp_f32_e32 v38, v34
	v_exp_f32_e32 v34, v39
	v_add_f32_e32 v35, 1.0, v35
	v_rcp_f32_e32 v100, v35
	v_exp_f32_e32 v35, v55
	v_add_f32_e32 v34, 1.0, v34
	v_rcp_f32_e32 v39, v34
	v_exp_f32_e32 v34, v40
	v_add_f32_e32 v35, 1.0, v35
	v_rcp_f32_e32 v101, v35
	v_exp_f32_e32 v35, v56
	v_add_f32_e32 v34, 1.0, v34
	v_rcp_f32_e32 v40, v34
	v_exp_f32_e32 v34, v41
	v_add_f32_e32 v35, 1.0, v35
	v_rcp_f32_e32 v102, v35
	v_exp_f32_e32 v35, v57
	v_add_f32_e32 v34, 1.0, v34
	v_rcp_f32_e32 v41, v34
	v_exp_f32_e32 v34, v42
	v_add_f32_e32 v35, 1.0, v35
	v_rcp_f32_e32 v103, v35
	v_exp_f32_e32 v35, v58
	v_add_f32_e32 v34, 1.0, v34
	v_rcp_f32_e32 v42, v34
	v_exp_f32_e32 v34, v43
	v_add_f32_e32 v35, 1.0, v35
	v_rcp_f32_e32 v54, v35
	v_exp_f32_e32 v35, v59
	v_add_f32_e32 v34, 1.0, v34
	v_rcp_f32_e32 v43, v34
	v_exp_f32_e32 v34, v44
	v_add_f32_e32 v35, 1.0, v35
	v_rcp_f32_e32 v55, v35
	v_exp_f32_e32 v35, v60
	v_add_f32_e32 v34, 1.0, v34
	v_rcp_f32_e32 v44, v34
	v_exp_f32_e32 v34, v45
	v_add_f32_e32 v35, 1.0, v35
	v_rcp_f32_e32 v56, v35
	v_exp_f32_e32 v35, v61
	v_add_f32_e32 v34, 1.0, v34
	v_rcp_f32_e32 v45, v34
	v_exp_f32_e32 v34, v46
	v_add_f32_e32 v35, 1.0, v35
	v_rcp_f32_e32 v57, v35
	v_exp_f32_e32 v35, v62
	v_add_f32_e32 v34, 1.0, v34
	v_rcp_f32_e32 v46, v34
	v_exp_f32_e32 v34, v47
	v_exp_f32_e32 v37, v63
	v_add_f32_e32 v35, 1.0, v35
	v_rcp_f32_e32 v35, v35
	v_add_f32_e32 v34, 1.0, v34
	v_rcp_f32_e32 v36, v34
	v_add_f32_e32 v34, 1.0, v37
	v_rcp_f32_e32 v34, v34
	s_cbranch_scc1 .LBB0_464
	v_add_u32_e32 v37, s27, v64
	v_add_u32_e32 v47, 32, v37
	v_cmp_lt_i32_e64 s[76:77], v47, v109
	v_add_u32_e32 v47, 1, v37
	v_cmp_lt_i32_e64 s[66:67], v47, v109
	v_add_u32_e32 v47, 33, v37
	v_cmp_lt_i32_e64 s[42:43], v47, v109
	v_add_u32_e32 v47, 2, v37
	v_cmp_lt_i32_e64 s[70:71], v47, v109
	v_add_u32_e32 v47, 34, v37
	v_cmp_lt_i32_e64 s[44:45], v47, v109
	v_add_u32_e32 v47, 3, v37
	v_cmp_lt_i32_e64 s[74:75], v47, v109
	v_add_u32_e32 v47, 35, v37
	v_cmp_lt_i32_e64 s[46:47], v47, v109
	v_add_u32_e32 v47, 4, v37
	v_cmp_lt_i32_e64 s[78:79], v47, v109
	v_add_u32_e32 v47, 36, v37
	v_cmp_lt_i32_e64 s[48:49], v47, v109
	v_add_u32_e32 v47, 5, v37
	v_cmp_lt_i32_e64 s[80:81], v47, v109
	v_add_u32_e32 v47, 37, v37
	v_cmp_lt_i32_e64 s[50:51], v47, v109
	v_add_u32_e32 v47, 6, v37
	v_cmp_lt_i32_e64 s[82:83], v47, v109
	v_add_u32_e32 v47, 38, v37
	v_cmp_lt_i32_e64 s[52:53], v47, v109
	v_add_u32_e32 v47, 7, v37
	v_cmp_lt_i32_e64 s[84:85], v47, v109
	v_add_u32_e32 v47, 39, v37
	v_cmp_lt_i32_e64 s[54:55], v47, v109
	v_add_u32_e32 v47, 8, v37
	v_cmp_lt_i32_e64 s[86:87], v47, v109
	v_add_u32_e32 v47, 40, v37
	v_cmp_lt_i32_e64 s[56:57], v47, v109
	v_add_u32_e32 v47, 9, v37
	v_cmp_lt_i32_e64 s[88:89], v47, v109
	v_add_u32_e32 v47, 41, v37
	v_cmp_lt_i32_e64 s[58:59], v47, v109
	v_add_u32_e32 v47, 10, v37
	v_cmp_lt_i32_e64 s[90:91], v47, v109
	v_add_u32_e32 v47, 42, v37
	v_cmp_lt_i32_e64 s[60:61], v47, v109
	v_add_u32_e32 v47, 11, v37
;     ...
;             if (k0 + 63 >= qw) {
;                 const int kb0 = k0 + 16 * hi;
; #pragma unroll
;                 for (int r = 0; r < 16; ++r) { if (kb0 + r >= qrel) p0[r] = 1.f; if (kb0 + 32 + r >= qrel) p1[r] = 1.f; }
;             }
	v_cmp_lt_i32_e64 s[92:93], v47, v109
	v_add_u32_e32 v47, 43, v37
	v_cmp_lt_i32_e64 s[64:65], v47, v109
	v_add_u32_e32 v47, 12, v37
	v_cmp_lt_i32_e64 s[94:95], v47, v109
	v_add_u32_e32 v47, 44, v37
	v_cmp_lt_i32_e64 s[68:69], v47, v109
	v_add_u32_e32 v47, 13, v37
	v_cmp_lt_i32_e64 s[96:97], v47, v109
	v_add_u32_e32 v47, 45, v37
	v_cmp_lt_i32_e64 s[22:23], v47, v109
	v_add_u32_e32 v47, 14, v37
	v_cmp_lt_i32_e64 s[6:7], v47, v109
	v_add_u32_e32 v47, 46, v37
	v_cmp_lt_i32_e64 s[4:5], v47, v109
	v_add_u32_e32 v47, 15, v37
	v_cmp_lt_i32_e32 vcc, v47, v109
	v_cmp_lt_i32_e64 s[62:63], v37, v109
	v_add_u32_e32 v37, 47, v37
	v_cndmask_b32_e32 v36, 1.0, v36, vcc
	s_or_b64 vcc, vcc, s[6:7]
	v_cndmask_b32_e32 v46, 1.0, v46, vcc
	s_or_b64 vcc, vcc, s[96:97]
	v_cndmask_b32_e32 v45, 1.0, v45, vcc
	s_or_b64 vcc, vcc, s[94:95]
	v_cndmask_b32_e32 v44, 1.0, v44, vcc
	s_or_b64 vcc, vcc, s[92:93]
	v_cndmask_b32_e32 v43, 1.0, v43, vcc
	s_or_b64 vcc, vcc, s[90:91]
	v_cndmask_b32_e32 v42, 1.0, v42, vcc
	s_or_b64 vcc, vcc, s[88:89]
	v_cndmask_b32_e32 v41, 1.0, v41, vcc
	s_or_b64 vcc, vcc, s[86:87]
	v_cndmask_b32_e32 v40, 1.0, v40, vcc
	s_or_b64 vcc, vcc, s[84:85]
	v_cndmask_b32_e32 v39, 1.0, v39, vcc
	s_or_b64 vcc, vcc, s[82:83]
	v_cndmask_b32_e32 v38, 1.0, v38, vcc
	s_or_b64 vcc, vcc, s[80:81]
	v_cndmask_b32_e32 v51, 1.0, v51, vcc
	s_or_b64 vcc, vcc, s[78:79]
	v_cndmask_b32_e32 v50, 1.0, v50, vcc
	s_or_b64 vcc, vcc, s[74:75]
	v_cndmask_b32_e32 v49, 1.0, v49, vcc
	s_or_b64 vcc, vcc, s[70:71]
	v_cndmask_b32_e32 v48, 1.0, v48, vcc
	s_or_b64 vcc, vcc, s[66:67]
	v_cndmask_b32_e32 v33, 1.0, v33, vcc
	s_or_b64 vcc, vcc, s[62:63]
	v_cndmask_b32_e32 v32, 1.0, v32, vcc
	v_cmp_lt_i32_e32 vcc, v37, v109
	s_nop 1
	v_cndmask_b32_e32 v34, 1.0, v34, vcc
	s_or_b64 vcc, vcc, s[4:5]
	v_cndmask_b32_e32 v35, 1.0, v35, vcc
	s_or_b64 vcc, vcc, s[22:23]
	v_cndmask_b32_e32 v57, 1.0, v57, vcc
	s_or_b64 vcc, vcc, s[68:69]
	v_cndmask_b32_e32 v56, 1.0, v56, vcc
	s_or_b64 vcc, vcc, s[64:65]
	v_cndmask_b32_e32 v55, 1.0, v55, vcc
	s_or_b64 vcc, vcc, s[60:61]
	v_cndmask_b32_e32 v54, 1.0, v54, vcc
	s_or_b64 vcc, vcc, s[58:59]
	v_cndmask_b32_e32 v103, 1.0, v103, vcc
	s_or_b64 vcc, vcc, s[56:57]
	v_cndmask_b32_e32 v102, 1.0, v102, vcc
	s_or_b64 vcc, vcc, s[54:55]
	v_cndmask_b32_e32 v101, 1.0, v101, vcc
	s_or_b64 vcc, vcc, s[52:53]
	v_cndmask_b32_e32 v100, 1.0, v100, vcc
	s_or_b64 vcc, vcc, s[50:51]
	v_cndmask_b32_e32 v53, 1.0, v53, vcc
	s_or_b64 vcc, vcc, s[48:49]
	v_cndmask_b32_e32 v52, 1.0, v52, vcc
	s_or_b64 vcc, vcc, s[46:47]
	v_cndmask_b32_e32 v99, 1.0, v99, vcc
	s_or_b64 vcc, vcc, s[44:45]
	v_cndmask_b32_e32 v98, 1.0, v98, vcc
	s_or_b64 vcc, vcc, s[42:43]
	v_cndmask_b32_e32 v97, 1.0, v97, vcc
	s_or_b64 vcc, vcc, s[76:77]
	v_cndmask_b32_e32 v96, 1.0, v96, vcc
; #define LAS __attribute__((address_space(3)))
; __device__ __forceinline__ unsigned pk2(float lo, float hi) { return pg8::cvt_pk_bf16(lo, hi); }
; #define AT_PV(W, off) do { const bf16x8 pf_ = __builtin_bit_cast(bf16x8, W); \
;                 const bf16x8 v0_ = *(const LAS bf16x8*)(vb + (off)), v1_ = *(const LAS bf16x8*)(vb + 4608 + (off)); \
;                 o0 = __builtin_amdgcn_mfma_f32_32x32x16_bf16(v0_, pf_, o0, 0, 0, 0); o1 = __builtin_amdgcn_mfma_f32_32x32x16_bf16(v1_, pf_, o1, 0, 0, 0); } while (0)
;     ...
; #pragma unroll
;             for (int r = 14; r >= 0; --r) { p0[r] *= p0[r + 1]; p1[r] *= p1[r + 1]; }
;             const float L0 = p0[0], L1 = p1[0];
;             const float pL0 = __shfl_xor(L0, 32), pL1 = __shfl_xor(L1, 32);
;             const float tot1 = L1 * pL1;
;             const float pre1 = hi ? C : C * pL1;
;             const float pre0 = C * tot1 * (hi ? 1.f : pL0);
;             C = C * tot1 * (L0 * pL0);
; #pragma unroll
;             for (int r = 0; r < 15; ++r) { p0[r] = pre0 * (p0[r + 1] - p0[r]); p1[r] = pre1 * (p1[r + 1] - p1[r]); }
;             p0[15] = pre0 * (1.f - p0[15]); p1[15] = pre1 * (1.f - p1[15]);
;             u32x4 w00, w01, w10, w11;
;             w00.x = pk2(p0[0], p0[1]); w00.y = pk2(p0[2], p0[3]); w00.z = pk2(p0[4], p0[5]); w00.w = pk2(p0[6], p0[7]);
;             w01.x = pk2(p0[8], p0[9]); w01.y = pk2(p0[10], p0[11]); w01.z = pk2(p0[12], p0[13]); w01.w = pk2(p0[14], p0[15]);
;             w10.x = pk2(p1[0], p1[1]); w10.y = pk2(p1[2], p1[3]); w10.z = pk2(p1[4], p1[5]); w10.w = pk2(p1[6], p1[7]);
;             w11.x = pk2(p1[8], p1[9]); w11.y = pk2(p1[10], p1[11]); w11.z = pk2(p1[12], p1[13]); w11.w = pk2(p1[14], p1[15]);
;             const LAS unsigned char* vb = lds + AT_V + cur * 9216 + r32 * 144 + hi * 32;
;     ...
;             AT_PV(w00, 0); AT_PV(w01, 16); AT_PV(w10, 64); AT_PV(w11, 80);
.LBB0_464:
	v_and_b32_e32 v47, 64, v236
	v_xor_b32_e32 v37, 32, v236
	v_add_u32_e32 v47, 64, v47
	v_cmp_lt_i32_e32 vcc, v37, v47
	v_mov_b32_e32 v47, v57
	v_pk_mov_b32 v[56:57], v[44:45], v[56:57] op_sel:[1,0]
	v_cndmask_b32_e32 v37, v236, v37, vcc
	v_lshlrev_b32_e32 v94, 2, v37
	v_mul_f32_e32 v37, v35, v34
	v_pk_mul_f32 v[46:47], v[46:47], v[36:37]
	v_mov_b32_e32 v45, v55
	v_pk_mul_f32 v[56:57], v[56:57], v[46:47]
	v_mov_b32_e32 v58, v42
	v_pk_mul_f32 v[44:45], v[44:45], v[56:57]
	v_pk_mov_b32 v[42:43], v[42:43], v[54:55] op_sel:[1,0]
	v_mov_b32_e32 v59, v103
	v_pk_mul_f32 v[42:43], v[42:43], v[44:45]
	v_pk_mov_b32 v[60:61], v[40:41], v[102:103] op_sel:[1,0]
	v_pk_mul_f32 v[58:59], v[58:59], v[42:43]
	v_mov_b32_e32 v41, v101
	v_pk_mul_f32 v[60:61], v[60:61], v[58:59]
	v_pk_mov_b32 v[62:63], v[38:39], v[100:101] op_sel:[1,0]
	v_pk_mul_f32 v[40:41], v[40:41], v[60:61]
	v_mov_b32_e32 v39, v53
	v_pk_mul_f32 v[62:63], v[62:63], v[40:41]
	v_pk_mov_b32 v[52:53], v[50:51], v[52:53] op_sel:[1,0]
	v_pk_mul_f32 v[38:39], v[38:39], v[62:63]
	v_mov_b32_e32 v51, v99
	v_pk_mul_f32 v[52:53], v[52:53], v[38:39]
	v_pk_mov_b32 v[98:99], v[48:49], v[98:99] op_sel:[1,0]
	v_pk_mul_f32 v[50:51], v[50:51], v[52:53]
	v_mov_b32_e32 v49, v97
	v_pk_mul_f32 v[98:99], v[98:99], v[50:51]
	v_pk_mov_b32 v[96:97], v[32:33], v[96:97] op_sel:[1,0]
	v_pk_mul_f32 v[48:49], v[48:49], v[98:99]
	v_mov_b32_e32 v102, v56
	v_pk_mul_f32 v[96:97], v[96:97], v[48:49]
	ds_bpermute_b32 v33, v94, v97
	v_mov_b32_e32 v103, v46
	v_mov_b32_e32 v114, v45
	v_mov_b32_e32 v115, v57
	v_mov_b32_e32 v54, v43
	v_mov_b32_e32 v55, v45
	v_mov_b32_e32 v45, v56
	v_pk_add_f32 v[54:55], v[114:115], v[54:55] neg_lo:[0,1] neg_hi:[0,1]
	v_mov_b32_e32 v114, v57
	v_pk_add_f32 v[56:57], v[102:103], v[44:45] neg_lo:[0,1] neg_hi:[0,1]
	s_waitcnt lgkmcnt(0)
	v_pk_mul_f32 v[102:103], v[32:33], v[96:97]
	ds_bpermute_b32 v94, v94, v102
	v_mul_f32_e32 v32, v95, v33
	v_cndmask_b32_e64 v32, v95, v32, s[36:37]
	v_mov_b32_e32 v116, v96
	v_mov_b32_e32 v117, v48
	s_waitcnt lgkmcnt(0)
	v_cndmask_b32_e64 v33, 1.0, v94, s[36:37]
	v_pk_mul_f32 v[94:95], v[102:103], v[94:95]
	v_mov_b32_e32 v103, v96
	v_pk_add_f32 v[102:103], v[116:117], v[102:103] neg_lo:[0,1] neg_hi:[0,1]
	v_mov_b32_e32 v116, v49
	v_mov_b32_e32 v117, v99
	v_mov_b32_e32 v96, v97
	v_mov_b32_e32 v97, v49
	v_pk_add_f32 v[96:97], v[116:117], v[96:97] neg_lo:[0,1] neg_hi:[0,1]
	v_mov_b32_e32 v116, v98
	v_mov_b32_e32 v117, v50
	v_mov_b32_e32 v49, v98
	v_pk_add_f32 v[48:49], v[116:117], v[48:49] neg_lo:[0,1] neg_hi:[0,1]
	v_mov_b32_e32 v116, v51
	v_mov_b32_e32 v117, v53
	v_mov_b32_e32 v98, v99
	v_mov_b32_e32 v99, v51
	v_pk_add_f32 v[98:99], v[116:117], v[98:99] neg_lo:[0,1] neg_hi:[0,1]
	v_mov_b32_e32 v116, v52
	v_mov_b32_e32 v117, v38
	v_mov_b32_e32 v51, v52
	v_pk_add_f32 v[50:51], v[116:117], v[50:51] neg_lo:[0,1] neg_hi:[0,1]
	v_mov_b32_e32 v116, v39
	v_mov_b32_e32 v117, v63
	v_mov_b32_e32 v52, v53
	v_mov_b32_e32 v53, v39
	v_pk_add_f32 v[52:53], v[116:117], v[52:53] neg_lo:[0,1] neg_hi:[0,1]
	v_mov_b32_e32 v116, v62
	v_mov_b32_e32 v117, v40
	v_mov_b32_e32 v39, v62
	v_pk_add_f32 v[38:39], v[116:117], v[38:39] neg_lo:[0,1] neg_hi:[0,1]
	v_mov_b32_e32 v116, v41
	v_mov_b32_e32 v117, v61
	v_mov_b32_e32 v62, v63
	v_mov_b32_e32 v63, v41
	v_pk_add_f32 v[62:63], v[116:117], v[62:63] neg_lo:[0,1] neg_hi:[0,1]
	v_mov_b32_e32 v116, v60
	v_mov_b32_e32 v117, v58
	v_mov_b32_e32 v41, v60
	v_pk_add_f32 v[40:41], v[116:117], v[40:41] neg_lo:[0,1] neg_hi:[0,1]
	v_mov_b32_e32 v116, v59
	v_mov_b32_e32 v117, v43
	v_mov_b32_e32 v60, v61
	v_mov_b32_e32 v61, v59
	v_mov_b32_e32 v100, v47
	v_mov_b32_e32 v101, v37
	v_mov_b32_e32 v115, v47
	v_pk_add_f32 v[60:61], v[116:117], v[60:61] neg_lo:[0,1] neg_hi:[0,1]
	v_mov_b32_e32 v43, v44
	v_mov_b32_e32 v59, v42
	v_mov_b32_e32 v196, v36
	v_mov_b32_e32 v47, v36
	v_mov_b32_e32 v35, v197
	v_mov_b32_e32 v36, v37
	v_mov_b32_e32 v37, v34
	v_pk_add_f32 v[100:101], v[100:101], v[114:115] neg_lo:[0,1] neg_hi:[0,1]
	v_mul_f32_e32 v114, v33, v95
	v_pk_mul_f32 v[60:61], v[32:33], v[60:61] op_sel_hi:[0,1]
	v_pk_add_f32 v[42:43], v[42:43], v[58:59] neg_lo:[0,1] neg_hi:[0,1]
	v_pk_add_f32 v[44:45], v[196:197], v[46:47] neg_lo:[0,1] neg_hi:[0,1]
	v_pk_add_f32 v[34:35], v[34:35], v[36:37] neg_lo:[0,1] neg_hi:[0,1]
	s_mul_i32 s4, s1, 0x2400
	v_pk_mul_f32 v[102:103], v[102:103], v[114:115] op_sel_hi:[1,0]
	v_pk_mul_f32 v[96:97], v[32:33], v[96:97] op_sel_hi:[0,1]
	v_pk_mul_f32 v[48:49], v[48:49], v[114:115] op_sel_hi:[1,0]
	v_pk_mul_f32 v[98:99], v[32:33], v[98:99] op_sel_hi:[0,1]
	v_pk_mul_f32 v[50:51], v[50:51], v[114:115] op_sel_hi:[1,0]
	v_pk_mul_f32 v[52:53], v[32:33], v[52:53] op_sel_hi:[0,1]
	v_pk_mul_f32 v[38:39], v[38:39], v[114:115] op_sel_hi:[1,0]
	v_pk_mul_f32 v[62:63], v[32:33], v[62:63] op_sel_hi:[0,1]
	v_pk_mul_f32 v[40:41], v[40:41], v[114:115] op_sel_hi:[1,0]
	v_pk_mul_f32 v[42:43], v[42:43], v[114:115] op_sel_hi:[1,0]
	v_pk_mul_f32 v[54:55], v[32:33], v[54:55] op_sel_hi:[0,1]
	v_pk_mul_f32 v[56:57], v[56:57], v[114:115] op_sel_hi:[1,0]
	v_pk_mul_f32 v[58:59], v[100:101], v[32:33] op_sel_hi:[1,0]
	v_pk_mul_f32 v[100:101], v[44:45], v[114:115] op_sel_hi:[1,0]
	v_pk_mul_f32 v[114:115], v[34:35], v[32:33] op_sel_hi:[1,0]
	v_cvt_pk_bf16_f32 v32, v60, v61
	v_add_u32_e32 v60, s4, v112
	v_cvt_pk_bf16_f32 v45, v48, v49
	v_cvt_pk_bf16_f32 v46, v50, v51
	v_cvt_pk_bf16_f32 v47, v38, v39
	v_cvt_pk_bf16_f32 v40, v40, v41
	v_cvt_pk_bf16_f32 v41, v42, v43
	v_cvt_pk_bf16_f32 v42, v56, v57
	v_cvt_pk_bf16_f32 v38, v52, v53
	v_cvt_pk_bf16_f32 v33, v54, v55
	v_cvt_pk_bf16_f32 v34, v58, v59
	v_cvt_pk_bf16_f32 v44, v102, v103
	v_cvt_pk_bf16_f32 v43, v100, v101
	v_cvt_pk_bf16_f32 v36, v96, v97
	s_waitcnt lgkmcnt(0)
	v_mfma_f32_32x32x16_bf16 v[16:31], v[206:209], v[44:47], v[16:31]
	v_cvt_pk_bf16_f32 v37, v98, v99
	v_cvt_pk_bf16_f32 v39, v62, v63
	v_cvt_pk_bf16_f32 v35, v114, v115
	v_mul_f32_e32 v95, v94, v95
	v_cmp_neq_f32_e32 vcc, 0, v95
	s_cmp_lg_u64 vcc, 0
	s_cselect_b64 s[4:5], -1, 0
	v_mfma_f32_32x32x16_bf16 v[0:15], v[210:213], v[44:47], v[0:15]
	v_mfma_f32_32x32x16_bf16 v[16:31], v[214:217], v[40:43], v[16:31]
	v_mfma_f32_32x32x16_bf16 v[0:15], v[218:221], v[40:43], v[0:15]
	v_mfma_f32_32x32x16_bf16 v[16:31], v[222:225], v[36:39], v[16:31]
	v_mfma_f32_32x32x16_bf16 v[0:15], v[226:229], v[36:39], v[0:15]
	v_mfma_f32_32x32x16_bf16 v[16:31], v[118:121], v[32:35], v[16:31]
	v_mfma_f32_32x32x16_bf16 v[0:15], v[122:125], v[32:35], v[0:15]
	v_cndmask_b32_e64 v32, 0, 1, s[4:5]
	s_andn2_b64 vcc, exec, s[12:13]
	s_cbranch_vccz .LBB0_472

; __global__ void __launch_bounds__(512, 2) fwd_kernel(Args a) {
	.amdhsa_kernel _Z10fwd_kernel4Args
		.amdhsa_group_segment_fixed_size 0
		.amdhsa_private_segment_fixed_size 0
		.amdhsa_kernarg_size 384
		.amdhsa_user_sgpr_count 2
		.amdhsa_user_sgpr_dispatch_ptr 0
		.amdhsa_user_sgpr_queue_ptr 0
		.amdhsa_user_sgpr_kernarg_segment_ptr 1
		.amdhsa_user_sgpr_dispatch_id 0
		.amdhsa_user_sgpr_kernarg_preload_length 0
		.amdhsa_user_sgpr_kernarg_preload_offset 0
		.amdhsa_user_sgpr_private_segment_size 0
		.amdhsa_uses_dynamic_stack 0
		.amdhsa_enable_private_segment 0
		.amdhsa_system_sgpr_workgroup_id_x 1
		.amdhsa_system_sgpr_workgroup_id_y 0
		.amdhsa_system_sgpr_workgroup_id_z 0
		.amdhsa_system_sgpr_workgroup_info 0
		.amdhsa_system_vgpr_workitem_id 2
		.amdhsa_next_free_vgpr 256
		.amdhsa_next_free_sgpr 100
		.amdhsa_accum_offset 256
		.amdhsa_reserve_vcc 1
		.amdhsa_float_round_mode_32 0
		.amdhsa_float_round_mode_16_64 0
		.amdhsa_float_denorm_mode_32 3
		.amdhsa_float_denorm_mode_16_64 3
		.amdhsa_dx10_clamp 1
		.amdhsa_ieee_mode 1
		.amdhsa_fp16_overflow 0
		.amdhsa_tg_split 0
		.amdhsa_exception_fp_ieee_invalid_op 0
		.amdhsa_exception_fp_denorm_src 0
		.amdhsa_exception_fp_ieee_div_zero 0
		.amdhsa_exception_fp_ieee_overflow 0
		.amdhsa_exception_fp_ieee_underflow 0
		.amdhsa_exception_fp_ieee_inexact 0
		.amdhsa_exception_int_div_zero 0
	.end_amdhsa_kernel

; __global__ void __launch_bounds__(512, 2) fwd_kernel(Args a) {
amdhsa.kernels:
  - .agpr_count:     0
    .args:
      - .offset:         0
        .size:           128
        .value_kind:     by_value
      - .offset:         128
        .size:           4
        .value_kind:     hidden_block_count_x
      - .offset:         132
        .size:           4
        .value_kind:     hidden_block_count_y
      - .offset:         136
        .size:           4
        .value_kind:     hidden_block_count_z
      - .offset:         140
        .size:           2
        .value_kind:     hidden_group_size_x
      - .offset:         142
        .size:           2
        .value_kind:     hidden_group_size_y
      - .offset:         144
        .size:           2
        .value_kind:     hidden_group_size_z
      - .offset:         146
        .size:           2
        .value_kind:     hidden_remainder_x
      - .offset:         148
        .size:           2
        .value_kind:     hidden_remainder_y
      - .offset:         150
        .size:           2
        .value_kind:     hidden_remainder_z
      - .offset:         168
        .size:           8
        .value_kind:     hidden_global_offset_x
      - .offset:         176
        .size:           8
        .value_kind:     hidden_global_offset_y
      - .offset:         184
        .size:           8
        .value_kind:     hidden_global_offset_z
      - .offset:         192
        .size:           2
        .value_kind:     hidden_grid_dims
      - .offset:         216
        .size:           8
        .value_kind:     hidden_multigrid_sync_arg
      - .offset:         248
        .size:           4
        .value_kind:     hidden_dynamic_lds_size
    .group_segment_fixed_size: 0
    .kernarg_segment_align: 8
    .kernarg_segment_size: 384
    .language:       OpenCL C
    .language_version:
      - 2
      - 0
    .max_flat_workgroup_size: 512
    .name:           _Z10fwd_kernel4Args
    .private_segment_fixed_size: 0
    .sgpr_count:     106
    .sgpr_spill_count: 269
    .symbol:         _Z10fwd_kernel4Args.kd
    .uniform_work_group_size: 1
    .uses_dynamic_stack: false
    .vgpr_count:     256
    .vgpr_spill_count: 0
    .wavefront_size: 64
